# first grid barrier: arrivals stay on the cooperative-groups word but waiters poll a separate release word detected by change of value (no pollers on the arrival counter)
# baseline (speedup 1.0000x reference)
; #define SEAM(k) do { if (IN(k) && IN((k) + 1)) grid.sync(); } while (0)
; __global__ void __launch_bounds__(512, 2) mega(Args args) {
;     ...
;     SEAM(0);
.LBB0_140:
	s_load_dwordx4 s[4:7], s[0:1], 0x80
	v_lshrrev_b32_e32 v177, 20, v0
	v_lshrrev_b32_e32 v213, 10, v0
	s_waitcnt lgkmcnt(0)
	v_writelane_b32 v252, s4, 30
	s_nop 1
	v_writelane_b32 v252, s5, 31
	v_writelane_b32 v252, s6, 32
	v_writelane_b32 v252, s7, 33
	s_nop 0
	v_readlane_b32 s0, v252, 22
	v_readlane_b32 s3, v252, 25
	v_readlane_b32 s1, v252, 23
	s_cmp_gt_i32 s3, 1
	v_readlane_b32 s2, v252, 24
	s_cselect_b64 s[0:1], -1, 0
	s_and_b64 s[2:3], s[18:19], s[0:1]
	s_andn2_b64 vcc, exec, s[2:3]
	s_cbranch_vccnz .LBB0_152
	v_or_b32_e32 v0, v213, v177
	s_movk_i32 s2, 0x3ff
	v_and_or_b32 v0, v0, s2, v176
	v_cmp_eq_u32_e32 vcc, 0, v0
	s_barrier
	s_and_saveexec_b64 s[2:3], vcc
	s_cbranch_execz .LBB0_151
	buffer_wbl2 sc1
	s_waitcnt vmcnt(0)
	s_load_dwordx2 s[4:5], s[74:75], 0x58
	v_readlane_b32 s10, v252, 22
	v_readlane_b32 s11, v252, 23
	s_add_u32 s10, s10, 0x2800000
	s_addc_u32 s11, s11, 0
	v_mov_b32_e32 v2, 0
	s_nop 3
	global_load_dword v1, v2, s[10:11] sc1
	s_waitcnt lgkmcnt(0)
	global_load_dword v0, v2, s[4:5] offset:40
	s_waitcnt vmcnt(0)
	v_mov_b32_e32 v3, 1
	global_atomic_add v3, v2, v3, s[4:5] offset:32 sc0
	s_waitcnt vmcnt(0)
	v_readfirstlane_b32 s6, v3
	v_readfirstlane_b32 s7, v0
	v_readfirstlane_b32 s8, v1
	s_nop 3
	s_and_b32 s6, s6, 0xffff
	s_add_i32 s9, s7, -1
	s_cmp_lg_u32 s6, s9
	s_cbranch_scc1 .Lgb0_poll
	s_sub_i32 s9, 0x10000, s7
	v_mov_b32_e32 v0, s9
	global_atomic_add v2, v0, s[4:5] offset:32
	v_mov_b32_e32 v0, 1
	s_nop 0
	global_atomic_add v2, v0, s[10:11]
	s_branch .Lgb0_done
.Lgb0_poll:
	global_load_dword v0, v2, s[10:11] sc1
	s_waitcnt vmcnt(0)
	v_readfirstlane_b32 s6, v0
	s_nop 3
	s_cmp_lg_u32 s6, s8
	s_cbranch_scc1 .Lgb0_done
	s_sleep 1
	s_branch .Lgb0_poll
